# k14
# speedup vs baseline: 1.0053x; 1.0053x over previous
; __device__ __forceinline__ unsigned cvtpk(float lo, float hi) { f32x2 v = {lo, hi}; bf16x2_t b = __builtin_convertvector(v, bf16x2_t); return __builtin_bit_cast(unsigned, b); }
;     __device__ __forceinline__ void operator()(const f32x4 (&acc)[2][2][4][2], const Unit& u, int ui, int wr, int wc, int fr, int fq) const {
;     ...
;             for (int m = 0; m < 4; ++m) { const int rl = ai * HALF + wr * 64 + m * 16 + fr; const float rs = rsl[(ui & 1) * 256 + rl];
;                 float h[8];
; #pragma unroll
;                 for (int n = 0; n < 2; ++n)
; #pragma unroll
;                     for (int e = 0; e < 4; ++e) { const float g = acc[ai][0][m][n][e] * rs, up = acc[ai][1][m][n][e] * rs;
;                         h[n * 4 + e] = g * __builtin_amdgcn_rcpf(1.f + __builtin_amdgcn_exp2f(-g * LOG2E)) * up; }
;                 u32x4 w; w.x = cvtpk(h[0], h[1]); w.y = cvtpk(h[2], h[3]); w.z = cvtpk(h[4], h[5]); w.w = cvtpk(h[6], h[7]);
;                 *(u32x4*)(H + (size_t)(u.pm * 256 + rl) * DFF + col0) = w; }
.Lffnup_pf_skip:
	v_mbcnt_lo_u32_b32 v141, -1, 0
	v_mbcnt_hi_u32_b32 v141, -1, v141
	s_lshl_b32 s12, s38, 7
	v_ashrrev_i32_e32 v140, 1, v141
	s_or_b32 s12, s12, s69
	v_and_b32_e32 v140, -8, v140
	v_add_u32_e32 v140, s12, v140
	s_lshl_b32 s12, s37, 10
	s_and_b32 s12, s12, 0x400
	v_and_or_b32 v147, v141, 15, s68
	s_add_i32 s12, s12, 0
	v_lshl_add_u32 v142, v147, 2, s12
	v_add_u32_e32 v146, 0x20000, v142
	ds_read2_b32 v[142:143], v146 offset1:16
	v_ashrrev_i32_e32 v141, 31, v140
	s_andn2_b64 vcc, exec, s[4:5]
	s_waitcnt lgkmcnt(0)
	v_mul_f32_e32 v170, 0xbfb8aa3b, v142
	v_mul_f32_e32 v172, v142, v142
	v_pk_mul_f32 v[182:183], v[126:127], v[122:123]
	v_pk_mul_f32 v[184:185], v[128:129], v[124:125]
	v_pk_mul_f32 v[186:187], v[118:119], v[114:115]
	v_pk_mul_f32 v[188:189], v[120:121], v[116:117]
	v_rcp_f32_e32 v172, v172
	v_pk_mul_f32 v[174:175], v[126:127], v[170:171] op_sel_hi:[1,0]
	v_pk_mul_f32 v[176:177], v[128:129], v[170:171] op_sel_hi:[1,0]
	v_pk_mul_f32 v[178:179], v[118:119], v[170:171] op_sel_hi:[1,0]
	v_pk_mul_f32 v[180:181], v[120:121], v[170:171] op_sel_hi:[1,0]
	v_exp_f32_e32 v174, v174
	v_exp_f32_e32 v175, v175
	v_exp_f32_e32 v176, v176
	v_exp_f32_e32 v177, v177
	v_exp_f32_e32 v178, v178
	v_exp_f32_e32 v179, v179
	v_exp_f32_e32 v180, v180
	v_exp_f32_e32 v181, v181
	v_pk_fma_f32 v[174:175], v[174:175], v[172:173], v[172:173] op_sel_hi:[1,0,0]
	v_pk_fma_f32 v[176:177], v[176:177], v[172:173], v[172:173] op_sel_hi:[1,0,0]
	v_pk_fma_f32 v[178:179], v[178:179], v[172:173], v[172:173] op_sel_hi:[1,0,0]
	v_pk_fma_f32 v[180:181], v[180:181], v[172:173], v[172:173] op_sel_hi:[1,0,0]
	v_rcp_f32_e32 v174, v174
	v_rcp_f32_e32 v175, v175
	v_rcp_f32_e32 v176, v176
	v_rcp_f32_e32 v177, v177
	v_rcp_f32_e32 v178, v178
	v_rcp_f32_e32 v179, v179
	v_rcp_f32_e32 v180, v180
	v_rcp_f32_e32 v181, v181
	v_pk_mul_f32 v[182:183], v[182:183], v[174:175]
	v_pk_mul_f32 v[184:185], v[184:185], v[176:177]
	v_pk_mul_f32 v[186:187], v[186:187], v[178:179]
	v_pk_mul_f32 v[188:189], v[188:189], v[180:181]
	v_lshl_add_u32 v118, s36, 8, v147
	v_mov_b64_e32 v[114:115], s[10:11]
	v_mad_i64_i32 v[124:125], s[34:35], v118, s55, v[114:115]
	v_lshlrev_b64 v[116:117], 1, v[140:141]
	v_lshl_add_u64 v[124:125], v[124:125], 0, v[116:117]
	v_cvt_pk_bf16_f32 v120, v182, v183
	v_cvt_pk_bf16_f32 v121, v184, v185
	v_cvt_pk_bf16_f32 v122, v186, v187
	v_cvt_pk_bf16_f32 v123, v188, v189
	global_store_dwordx4 v[124:125], v[120:123], off
	s_mov_b64 s[36:37], -1
	s_nop 0
	v_mul_f32_e32 v170, 0xbfb8aa3b, v143
	v_mul_f32_e32 v172, v143, v143
	v_pk_mul_f32 v[182:183], v[110:111], v[106:107]
	v_pk_mul_f32 v[184:185], v[112:113], v[108:109]
	v_pk_mul_f32 v[186:187], v[102:103], v[98:99]
	v_pk_mul_f32 v[188:189], v[104:105], v[100:101]
	v_rcp_f32_e32 v172, v172
	v_pk_mul_f32 v[174:175], v[110:111], v[170:171] op_sel_hi:[1,0]
	v_pk_mul_f32 v[176:177], v[112:113], v[170:171] op_sel_hi:[1,0]
	v_pk_mul_f32 v[178:179], v[102:103], v[170:171] op_sel_hi:[1,0]
	v_pk_mul_f32 v[180:181], v[104:105], v[170:171] op_sel_hi:[1,0]
	v_exp_f32_e32 v174, v174
	v_exp_f32_e32 v175, v175
	v_exp_f32_e32 v176, v176
	v_exp_f32_e32 v177, v177
	v_exp_f32_e32 v178, v178
	v_exp_f32_e32 v179, v179
	v_exp_f32_e32 v180, v180
	v_exp_f32_e32 v181, v181
	v_pk_fma_f32 v[174:175], v[174:175], v[172:173], v[172:173] op_sel_hi:[1,0,0]
	v_pk_fma_f32 v[176:177], v[176:177], v[172:173], v[172:173] op_sel_hi:[1,0,0]
	v_pk_fma_f32 v[178:179], v[178:179], v[172:173], v[172:173] op_sel_hi:[1,0,0]
	v_pk_fma_f32 v[180:181], v[180:181], v[172:173], v[172:173] op_sel_hi:[1,0,0]
	v_rcp_f32_e32 v174, v174
	v_rcp_f32_e32 v175, v175
	v_rcp_f32_e32 v176, v176
	v_rcp_f32_e32 v177, v177
	v_rcp_f32_e32 v178, v178
	v_rcp_f32_e32 v179, v179
	v_rcp_f32_e32 v180, v180
	v_rcp_f32_e32 v181, v181
	v_pk_mul_f32 v[182:183], v[182:183], v[174:175]
	v_pk_mul_f32 v[184:185], v[184:185], v[176:177]
	v_pk_mul_f32 v[186:187], v[186:187], v[178:179]
	v_pk_mul_f32 v[188:189], v[188:189], v[180:181]
	v_add_u32_e32 v102, 16, v118
	v_mad_i64_i32 v[102:103], s[34:35], v102, s55, v[114:115]
	v_lshl_add_u64 v[102:103], v[102:103], 0, v[116:117]
	v_cvt_pk_bf16_f32 v98, v182, v183
	v_cvt_pk_bf16_f32 v99, v184, v185
	v_cvt_pk_bf16_f32 v100, v186, v187
	v_cvt_pk_bf16_f32 v101, v188, v189
	global_store_dwordx4 v[102:103], v[98:101], off
	ds_read2_b32 v[98:99], v146 offset0:32 offset1:48
	s_waitcnt lgkmcnt(0)
; __device__ __forceinline__ unsigned cvtpk(float lo, float hi) { f32x2 v = {lo, hi}; bf16x2_t b = __builtin_convertvector(v, bf16x2_t); return __builtin_bit_cast(unsigned, b); }
;     __device__ __forceinline__ void operator()(const f32x4 (&acc)[2][2][4][2], const Unit& u, int ui, int wr, int wc, int fr, int fq) const {
;     ...
;             for (int m = 0; m < 4; ++m) { const int rl = ai * HALF + wr * 64 + m * 16 + fr; const float rs = rsl[(ui & 1) * 256 + rl];
;                 float h[8];
; #pragma unroll
;                 for (int n = 0; n < 2; ++n)
; #pragma unroll
;                     for (int e = 0; e < 4; ++e) { const float g = acc[ai][0][m][n][e] * rs, up = acc[ai][1][m][n][e] * rs;
;                         h[n * 4 + e] = g * __builtin_amdgcn_rcpf(1.f + __builtin_amdgcn_exp2f(-g * LOG2E)) * up; }
;                 u32x4 w; w.x = cvtpk(h[0], h[1]); w.y = cvtpk(h[2], h[3]); w.z = cvtpk(h[4], h[5]); w.w = cvtpk(h[6], h[7]);
;                 *(u32x4*)(H + (size_t)(u.pm * 256 + rl) * DFF + col0) = w; }
	v_mul_f32_e32 v170, 0xbfb8aa3b, v98
	v_mul_f32_e32 v172, v98, v98
	v_pk_mul_f32 v[182:183], v[94:95], v[90:91]
	v_pk_mul_f32 v[184:185], v[96:97], v[92:93]
	v_pk_mul_f32 v[186:187], v[86:87], v[82:83]
	v_pk_mul_f32 v[188:189], v[88:89], v[84:85]
	v_rcp_f32_e32 v172, v172
	v_pk_mul_f32 v[174:175], v[94:95], v[170:171] op_sel_hi:[1,0]
	v_pk_mul_f32 v[176:177], v[96:97], v[170:171] op_sel_hi:[1,0]
	v_pk_mul_f32 v[178:179], v[86:87], v[170:171] op_sel_hi:[1,0]
	v_pk_mul_f32 v[180:181], v[88:89], v[170:171] op_sel_hi:[1,0]
	v_exp_f32_e32 v174, v174
	v_exp_f32_e32 v175, v175
	v_exp_f32_e32 v176, v176
	v_exp_f32_e32 v177, v177
	v_exp_f32_e32 v178, v178
	v_exp_f32_e32 v179, v179
	v_exp_f32_e32 v180, v180
	v_exp_f32_e32 v181, v181
	v_pk_fma_f32 v[174:175], v[174:175], v[172:173], v[172:173] op_sel_hi:[1,0,0]
	v_pk_fma_f32 v[176:177], v[176:177], v[172:173], v[172:173] op_sel_hi:[1,0,0]
	v_pk_fma_f32 v[178:179], v[178:179], v[172:173], v[172:173] op_sel_hi:[1,0,0]
	v_pk_fma_f32 v[180:181], v[180:181], v[172:173], v[172:173] op_sel_hi:[1,0,0]
	v_rcp_f32_e32 v174, v174
	v_rcp_f32_e32 v175, v175
	v_rcp_f32_e32 v176, v176
	v_rcp_f32_e32 v177, v177
	v_rcp_f32_e32 v178, v178
	v_rcp_f32_e32 v179, v179
	v_rcp_f32_e32 v180, v180
	v_rcp_f32_e32 v181, v181
	v_pk_mul_f32 v[182:183], v[182:183], v[174:175]
	v_pk_mul_f32 v[184:185], v[184:185], v[176:177]
	v_pk_mul_f32 v[186:187], v[186:187], v[178:179]
	v_pk_mul_f32 v[188:189], v[188:189], v[180:181]
	v_add_u32_e32 v86, 32, v118
	v_mad_i64_i32 v[86:87], s[34:35], v86, s55, v[114:115]
	v_lshl_add_u64 v[86:87], v[86:87], 0, v[116:117]
	v_cvt_pk_bf16_f32 v82, v182, v183
	v_cvt_pk_bf16_f32 v83, v184, v185
	v_cvt_pk_bf16_f32 v84, v186, v187
	v_cvt_pk_bf16_f32 v85, v188, v189
	global_store_dwordx4 v[86:87], v[82:85], off
	s_nop 1
	v_mul_f32_e32 v170, 0xbfb8aa3b, v99
	v_mul_f32_e32 v172, v99, v99
	v_pk_mul_f32 v[182:183], v[78:79], v[74:75]
	v_pk_mul_f32 v[184:185], v[80:81], v[76:77]
	v_pk_mul_f32 v[186:187], v[70:71], v[66:67]
	v_pk_mul_f32 v[188:189], v[72:73], v[68:69]
	v_rcp_f32_e32 v172, v172
	v_pk_mul_f32 v[174:175], v[78:79], v[170:171] op_sel_hi:[1,0]
	v_pk_mul_f32 v[176:177], v[80:81], v[170:171] op_sel_hi:[1,0]
	v_pk_mul_f32 v[178:179], v[70:71], v[170:171] op_sel_hi:[1,0]
	v_pk_mul_f32 v[180:181], v[72:73], v[170:171] op_sel_hi:[1,0]
	v_exp_f32_e32 v174, v174
	v_exp_f32_e32 v175, v175
	v_exp_f32_e32 v176, v176
	v_exp_f32_e32 v177, v177
	v_exp_f32_e32 v178, v178
	v_exp_f32_e32 v179, v179
	v_exp_f32_e32 v180, v180
	v_exp_f32_e32 v181, v181
	v_pk_fma_f32 v[174:175], v[174:175], v[172:173], v[172:173] op_sel_hi:[1,0,0]
	v_pk_fma_f32 v[176:177], v[176:177], v[172:173], v[172:173] op_sel_hi:[1,0,0]
	v_pk_fma_f32 v[178:179], v[178:179], v[172:173], v[172:173] op_sel_hi:[1,0,0]
	v_pk_fma_f32 v[180:181], v[180:181], v[172:173], v[172:173] op_sel_hi:[1,0,0]
	v_rcp_f32_e32 v174, v174
	v_rcp_f32_e32 v175, v175
	v_rcp_f32_e32 v176, v176
	v_rcp_f32_e32 v177, v177
	v_rcp_f32_e32 v178, v178
	v_rcp_f32_e32 v179, v179
	v_rcp_f32_e32 v180, v180
	v_rcp_f32_e32 v181, v181
	v_pk_mul_f32 v[182:183], v[182:183], v[174:175]
	v_pk_mul_f32 v[184:185], v[184:185], v[176:177]
	v_pk_mul_f32 v[186:187], v[186:187], v[178:179]
	v_pk_mul_f32 v[188:189], v[188:189], v[180:181]
	v_add_u32_e32 v70, 48, v118
	v_mad_i64_i32 v[70:71], s[34:35], v70, s55, v[114:115]
	v_lshl_add_u64 v[70:71], v[70:71], 0, v[116:117]
	v_cvt_pk_bf16_f32 v66, v182, v183
	v_cvt_pk_bf16_f32 v67, v184, v185
	v_cvt_pk_bf16_f32 v68, v186, v187
	v_cvt_pk_bf16_f32 v69, v188, v189
	global_store_dwordx4 v[70:71], v[66:69], off
	ds_read2_b32 v[66:67], v146 offset0:128 offset1:144
	s_waitcnt lgkmcnt(0)
	v_mul_f32_e32 v170, 0xbfb8aa3b, v66
	v_mul_f32_e32 v172, v66, v66
	v_pk_mul_f32 v[182:183], v[62:63], v[58:59]
	v_pk_mul_f32 v[184:185], v[64:65], v[60:61]
	v_pk_mul_f32 v[186:187], v[54:55], v[50:51]
	v_pk_mul_f32 v[188:189], v[56:57], v[52:53]
	v_rcp_f32_e32 v172, v172
	v_pk_mul_f32 v[174:175], v[62:63], v[170:171] op_sel_hi:[1,0]
	v_pk_mul_f32 v[176:177], v[64:65], v[170:171] op_sel_hi:[1,0]
	v_pk_mul_f32 v[178:179], v[54:55], v[170:171] op_sel_hi:[1,0]
	v_pk_mul_f32 v[180:181], v[56:57], v[170:171] op_sel_hi:[1,0]
	v_exp_f32_e32 v174, v174
	v_exp_f32_e32 v175, v175
	v_exp_f32_e32 v176, v176
	v_exp_f32_e32 v177, v177
	v_exp_f32_e32 v178, v178
	v_exp_f32_e32 v179, v179
	v_exp_f32_e32 v180, v180
	v_exp_f32_e32 v181, v181
	v_pk_fma_f32 v[174:175], v[174:175], v[172:173], v[172:173] op_sel_hi:[1,0,0]
	v_pk_fma_f32 v[176:177], v[176:177], v[172:173], v[172:173] op_sel_hi:[1,0,0]
	v_pk_fma_f32 v[178:179], v[178:179], v[172:173], v[172:173] op_sel_hi:[1,0,0]
	v_pk_fma_f32 v[180:181], v[180:181], v[172:173], v[172:173] op_sel_hi:[1,0,0]
	v_rcp_f32_e32 v174, v174
	v_rcp_f32_e32 v175, v175
	v_rcp_f32_e32 v176, v176
	v_rcp_f32_e32 v177, v177
	v_rcp_f32_e32 v178, v178
	v_rcp_f32_e32 v179, v179
	v_rcp_f32_e32 v180, v180
	v_rcp_f32_e32 v181, v181
	v_pk_mul_f32 v[182:183], v[182:183], v[174:175]
	v_pk_mul_f32 v[184:185], v[184:185], v[176:177]
	v_pk_mul_f32 v[186:187], v[186:187], v[178:179]
	v_pk_mul_f32 v[188:189], v[188:189], v[180:181]
	v_add_u32_e32 v54, 0x80, v118
	v_mad_i64_i32 v[54:55], s[34:35], v54, s55, v[114:115]
	v_lshl_add_u64 v[54:55], v[54:55], 0, v[116:117]
	v_cvt_pk_bf16_f32 v50, v182, v183
	v_cvt_pk_bf16_f32 v51, v184, v185
	v_cvt_pk_bf16_f32 v52, v186, v187
	v_cvt_pk_bf16_f32 v53, v188, v189
	global_store_dwordx4 v[54:55], v[50:53], off
	s_nop 1
	v_mul_f32_e32 v170, 0xbfb8aa3b, v67
	v_mul_f32_e32 v172, v67, v67
	v_pk_mul_f32 v[182:183], v[46:47], v[42:43]
	v_pk_mul_f32 v[184:185], v[48:49], v[44:45]
	v_pk_mul_f32 v[186:187], v[38:39], v[34:35]
; __device__ __forceinline__ unsigned cvtpk(float lo, float hi) { f32x2 v = {lo, hi}; bf16x2_t b = __builtin_convertvector(v, bf16x2_t); return __builtin_bit_cast(unsigned, b); }
; __device__ __forceinline__ void rs_prep(const float* ssq, int tok0, LAS float* rsl, int ui, int wv) {
;     ...
;     if (tid < 256) { const f32x4* s = (const f32x4*)(ssq + (size_t)(tok0 + tid) * 16); const f32x4 a = s[0], b = s[1], c = s[2], d = s[3];
;         const float t = ((a.x + a.y) + (a.z + a.w)) + ((b.x + b.y) + (b.z + b.w)) + ((c.x + c.y) + (c.z + c.w)) + ((d.x + d.y) + (d.z + d.w));
;         rsl[(ui & 1) * 256 + tid] = rsqrtf(t * (1.f / 1024.f) + EPS); }
;     __device__ __forceinline__ void operator()(const f32x4 (&acc)[2][2][4][2], const Unit& u, int ui, int wr, int wc, int fr, int fq) const {
;     ...
;             for (int m = 0; m < 4; ++m) { const int rl = ai * HALF + wr * 64 + m * 16 + fr; const float rs = rsl[(ui & 1) * 256 + rl];
;                 float h[8];
; #pragma unroll
;                 for (int n = 0; n < 2; ++n)
; #pragma unroll
;                     for (int e = 0; e < 4; ++e) { const float g = acc[ai][0][m][n][e] * rs, up = acc[ai][1][m][n][e] * rs;
;                         h[n * 4 + e] = g * __builtin_amdgcn_rcpf(1.f + __builtin_amdgcn_exp2f(-g * LOG2E)) * up; }
;                 u32x4 w; w.x = cvtpk(h[0], h[1]); w.y = cvtpk(h[2], h[3]); w.z = cvtpk(h[4], h[5]); w.w = cvtpk(h[6], h[7]);
;                 *(u32x4*)(H + (size_t)(u.pm * 256 + rl) * DFF + col0) = w; }
	v_pk_mul_f32 v[188:189], v[40:41], v[36:37]
	v_rcp_f32_e32 v172, v172
	v_pk_mul_f32 v[174:175], v[46:47], v[170:171] op_sel_hi:[1,0]
	v_pk_mul_f32 v[176:177], v[48:49], v[170:171] op_sel_hi:[1,0]
	v_pk_mul_f32 v[178:179], v[38:39], v[170:171] op_sel_hi:[1,0]
	v_pk_mul_f32 v[180:181], v[40:41], v[170:171] op_sel_hi:[1,0]
	v_exp_f32_e32 v174, v174
	v_exp_f32_e32 v175, v175
	v_exp_f32_e32 v176, v176
	v_exp_f32_e32 v177, v177
	v_exp_f32_e32 v178, v178
	v_exp_f32_e32 v179, v179
	v_exp_f32_e32 v180, v180
	v_exp_f32_e32 v181, v181
	v_pk_fma_f32 v[174:175], v[174:175], v[172:173], v[172:173] op_sel_hi:[1,0,0]
	v_pk_fma_f32 v[176:177], v[176:177], v[172:173], v[172:173] op_sel_hi:[1,0,0]
	v_pk_fma_f32 v[178:179], v[178:179], v[172:173], v[172:173] op_sel_hi:[1,0,0]
	v_pk_fma_f32 v[180:181], v[180:181], v[172:173], v[172:173] op_sel_hi:[1,0,0]
	v_rcp_f32_e32 v174, v174
	v_rcp_f32_e32 v175, v175
	v_rcp_f32_e32 v176, v176
	v_rcp_f32_e32 v177, v177
	v_rcp_f32_e32 v178, v178
	v_rcp_f32_e32 v179, v179
	v_rcp_f32_e32 v180, v180
	v_rcp_f32_e32 v181, v181
	v_pk_mul_f32 v[182:183], v[182:183], v[174:175]
	v_pk_mul_f32 v[184:185], v[184:185], v[176:177]
	v_pk_mul_f32 v[186:187], v[186:187], v[178:179]
	v_pk_mul_f32 v[188:189], v[188:189], v[180:181]
	v_add_u32_e32 v38, 0x90, v118
	v_mad_i64_i32 v[38:39], s[34:35], v38, s55, v[114:115]
	v_lshl_add_u64 v[38:39], v[38:39], 0, v[116:117]
	v_cvt_pk_bf16_f32 v34, v182, v183
	v_cvt_pk_bf16_f32 v35, v184, v185
	v_cvt_pk_bf16_f32 v36, v186, v187
	v_cvt_pk_bf16_f32 v37, v188, v189
	global_store_dwordx4 v[38:39], v[34:37], off
	ds_read2_b32 v[34:35], v146 offset0:160 offset1:176
	s_waitcnt lgkmcnt(0)
	v_mul_f32_e32 v170, 0xbfb8aa3b, v34
	v_mul_f32_e32 v172, v34, v34
	v_pk_mul_f32 v[182:183], v[30:31], v[26:27]
	v_pk_mul_f32 v[184:185], v[32:33], v[28:29]
	v_pk_mul_f32 v[186:187], v[22:23], v[18:19]
	v_pk_mul_f32 v[188:189], v[24:25], v[20:21]
	v_rcp_f32_e32 v172, v172
	v_pk_mul_f32 v[174:175], v[30:31], v[170:171] op_sel_hi:[1,0]
	v_pk_mul_f32 v[176:177], v[32:33], v[170:171] op_sel_hi:[1,0]
	v_pk_mul_f32 v[178:179], v[22:23], v[170:171] op_sel_hi:[1,0]
	v_pk_mul_f32 v[180:181], v[24:25], v[170:171] op_sel_hi:[1,0]
	v_exp_f32_e32 v174, v174
	v_exp_f32_e32 v175, v175
	v_exp_f32_e32 v176, v176
	v_exp_f32_e32 v177, v177
	v_exp_f32_e32 v178, v178
	v_exp_f32_e32 v179, v179
	v_exp_f32_e32 v180, v180
	v_exp_f32_e32 v181, v181
	v_pk_fma_f32 v[174:175], v[174:175], v[172:173], v[172:173] op_sel_hi:[1,0,0]
	v_pk_fma_f32 v[176:177], v[176:177], v[172:173], v[172:173] op_sel_hi:[1,0,0]
	v_pk_fma_f32 v[178:179], v[178:179], v[172:173], v[172:173] op_sel_hi:[1,0,0]
	v_pk_fma_f32 v[180:181], v[180:181], v[172:173], v[172:173] op_sel_hi:[1,0,0]
	v_rcp_f32_e32 v174, v174
	v_rcp_f32_e32 v175, v175
	v_rcp_f32_e32 v176, v176
	v_rcp_f32_e32 v177, v177
	v_rcp_f32_e32 v178, v178
	v_rcp_f32_e32 v179, v179
	v_rcp_f32_e32 v180, v180
	v_rcp_f32_e32 v181, v181
	v_pk_mul_f32 v[182:183], v[182:183], v[174:175]
	v_pk_mul_f32 v[184:185], v[184:185], v[176:177]
	v_pk_mul_f32 v[186:187], v[186:187], v[178:179]
	v_pk_mul_f32 v[188:189], v[188:189], v[180:181]
	v_add_u32_e32 v22, 0xa0, v118
	v_mad_i64_i32 v[22:23], s[34:35], v22, s55, v[114:115]
	v_lshl_add_u64 v[22:23], v[22:23], 0, v[116:117]
	v_cvt_pk_bf16_f32 v18, v182, v183
	v_cvt_pk_bf16_f32 v19, v184, v185
	v_cvt_pk_bf16_f32 v20, v186, v187
	v_cvt_pk_bf16_f32 v21, v188, v189
	global_store_dwordx4 v[22:23], v[18:21], off
	s_nop 1
	v_mul_f32_e32 v170, 0xbfb8aa3b, v35
	v_mul_f32_e32 v172, v35, v35
	v_pk_mul_f32 v[182:183], v[14:15], v[10:11]
	v_pk_mul_f32 v[184:185], v[16:17], v[12:13]
	v_pk_mul_f32 v[186:187], v[6:7], v[2:3]
	v_pk_mul_f32 v[188:189], v[8:9], v[4:5]
	v_rcp_f32_e32 v172, v172
	v_pk_mul_f32 v[174:175], v[14:15], v[170:171] op_sel_hi:[1,0]
	v_pk_mul_f32 v[176:177], v[16:17], v[170:171] op_sel_hi:[1,0]
	v_pk_mul_f32 v[178:179], v[6:7], v[170:171] op_sel_hi:[1,0]
	v_pk_mul_f32 v[180:181], v[8:9], v[170:171] op_sel_hi:[1,0]
	v_exp_f32_e32 v174, v174
	v_exp_f32_e32 v175, v175
	v_exp_f32_e32 v176, v176
	v_exp_f32_e32 v177, v177
	v_exp_f32_e32 v178, v178
	v_exp_f32_e32 v179, v179
	v_exp_f32_e32 v180, v180
	v_exp_f32_e32 v181, v181
	v_pk_fma_f32 v[174:175], v[174:175], v[172:173], v[172:173] op_sel_hi:[1,0,0]
	v_pk_fma_f32 v[176:177], v[176:177], v[172:173], v[172:173] op_sel_hi:[1,0,0]
	v_pk_fma_f32 v[178:179], v[178:179], v[172:173], v[172:173] op_sel_hi:[1,0,0]
	v_pk_fma_f32 v[180:181], v[180:181], v[172:173], v[172:173] op_sel_hi:[1,0,0]
	v_rcp_f32_e32 v174, v174
	v_rcp_f32_e32 v175, v175
	v_rcp_f32_e32 v176, v176
	v_rcp_f32_e32 v177, v177
	v_rcp_f32_e32 v178, v178
	v_rcp_f32_e32 v179, v179
	v_rcp_f32_e32 v180, v180
	v_rcp_f32_e32 v181, v181
	v_pk_mul_f32 v[182:183], v[182:183], v[174:175]
	v_pk_mul_f32 v[184:185], v[184:185], v[176:177]
	v_pk_mul_f32 v[186:187], v[186:187], v[178:179]
	v_pk_mul_f32 v[188:189], v[188:189], v[180:181]
	v_add_u32_e32 v6, 0xb0, v118
	v_mad_i64_i32 v[6:7], s[34:35], v6, s55, v[114:115]
	v_lshl_add_u64 v[6:7], v[6:7], 0, v[116:117]
	v_cvt_pk_bf16_f32 v2, v182, v183
	v_cvt_pk_bf16_f32 v3, v184, v185
	v_cvt_pk_bf16_f32 v4, v186, v187
	v_cvt_pk_bf16_f32 v5, v188, v189
	global_store_dwordx4 v[6:7], v[2:5], off
	s_cbranch_vccnz .LBB0_1159
	s_nop 0
	v_mbcnt_lo_u32_b32 v2, -1, 0
	v_mbcnt_hi_u32_b32 v2, -1, v2
	s_nop 0
	v_add_u32_e32 v2, s16, v2
	v_cmp_gt_i32_e32 vcc, s88, v2
	s_and_saveexec_b64 s[4:5], vcc
	s_cbranch_execz .LBB0_1169
	s_lshl_b32 s12, s82, 10
	s_and_b32 s12, s12, 0x400
	s_add_i32 s12, s12, 0
	v_lshl_add_u32 v2, v2, 2, s12
	v_add_u32_e32 v2, 0x20000, v2
	s_waitcnt vmcnt(8)
	v_mov_b64_e32 v[4:5], v[154:155]
	v_mov_b64_e32 v[6:7], v[156:157]
	v_mov_b64_e32 v[8:9], v[158:159]
	v_mov_b64_e32 v[10:11], v[160:161]
	v_mov_b64_e32 v[12:13], v[162:163]
	v_mov_b64_e32 v[14:15], v[164:165]
	v_mov_b64_e32 v[16:17], v[166:167]
	v_mov_b64_e32 v[18:19], v[168:169]
	v_add_f32_e32 v8, v8, v9
	v_add_f32_e32 v10, v10, v11
	v_mov_b32_e32 v20, v17
	v_mov_b32_e32 v21, v18
	v_mov_b32_e32 v17, v19
	v_mov_b32_e32 v18, v13
	v_mov_b32_e32 v19, v14
	v_mov_b32_e32 v13, v15
	v_pk_add_f32 v[16:17], v[20:21], v[16:17]
	v_pk_add_f32 v[12:13], v[18:19], v[12:13]
	v_pk_add_f32 v[16:17], v[16:17], v[16:17] op_sel:[0,1] op_sel_hi:[1,0]
	v_pk_add_f32 v[12:13], v[12:13], v[12:13] op_sel:[0,1] op_sel_hi:[1,0]
	v_mov_b32_e32 v17, v4
	v_mov_b32_e32 v13, v5
	v_mov_b32_e32 v9, v6
	v_mov_b32_e32 v11, v7
	v_pk_add_f32 v[4:5], v[16:17], v[12:13]
	v_pk_add_f32 v[6:7], v[8:9], v[10:11]
	s_nop 0
	v_pk_add_f32 v[4:5], v[4:5], v[6:7]
	s_nop 0
	v_add_f32_e32 v3, v4, v5
	v_fmamk_f32 v3, v3, 0x3a800000, v254
	v_cmp_gt_f32_e32 vcc, s56, v3
	v_mul_f32_e32 v4, 0x4b800000, v3
	s_nop 0
	v_cndmask_b32_e32 v3, v3, v4, vcc
	v_rsq_f32_e32 v3, v3
	s_nop 0
	v_mul_f32_e32 v4, 0x45800000, v3
	v_cndmask_b32_e32 v3, v3, v4, vcc
	ds_write_b32 v2, v3
